# static s_setprio 3 for waves 0-3 in the GEMM phases and also in recurrence pass 2 (phase s3)
# speedup vs baseline: 1.0003x; 1.0003x over previous
.LBB0_24:
	s_mov_b32 s72, s34
	v_readlane_b32 s20, v254, 0
	s_cmp_lg_u32 s70, 0
	s_mov_b64 s[2:3], -1
	s_cbranch_scc0 .LBB0_477
	s_add_i32 s2, s70, -1
	s_mul_hi_i32 s3, s2, 0x92492493
	s_add_i32 s3, s3, s2
	s_lshr_b32 s4, s3, 31
	s_ashr_i32 s3, s3, 2
	s_add_i32 s24, s3, s4
	s_mul_i32 s3, s24, 7
	s_sub_i32 s11, s2, s3
	s_setprio 0
	s_cmp_eq_u32 s11, 0
	s_cbranch_scc1 .Lsp_gemm
	s_cmp_lt_u32 s11, 3
	s_cbranch_scc1 .Lsp_done
